# P1 x-prep rewritten: 4 rows in flight per wave, modulation vectors hoisted per sequence (original loop kept for other grid sizes)
# speedup vs baseline: 1.0142x; 1.0011x over previous
; __device__ __forceinline__ unsigned cvt_pk_bf16(float lo, float hi) { const f2_t v = {lo, hi}; const bf2_t b = __builtin_convertvector(v, bf2_t); return __builtin_bit_cast(unsigned, b); }
; __global__ void __launch_bounds__(NTHR, 2) mega(Params p) {
;     ...
;     { const int wid = tid >> 6, lane = tid & 63;
;         for (int r = bid * 8 + wid; r < MTOK; r += G * 8) { const int seq = seq_of_row(r);
;             const float* xr = r < 16384 ? p.xp + (size_t)r * DM : p.xs + (size_t)(r - 16384) * DM; float s = 0.f; f32x4 v[4];
; #pragma unroll
;             for (int jj = 0; jj < 4; ++jj) { v[jj] = *(const f32x4*)(xr + jj * 256 + 4 * lane); s += (v[jj][0] * v[jj][0] + v[jj][1] * v[jj][1]) + (v[jj][2] * v[jj][2] + v[jj][3] * v[jj][3]); }
; #pragma unroll
;             for (int o = 32; o >= 1; o >>= 1) s += __shfl_xor(s, o);
;             if (lane == 0) ssb[r] = (u64)(s * SSK);
; #pragma unroll
;             for (int jj = 0; jj < 4; ++jj) { const int c = jj * 256 + 4 * lane; u32x2 wv; float h[4];
; #pragma unroll
;                 for (int j = 0; j < 4; ++j) h[j] = v[jj][j] * (p.norm_g[c + j] * (1.0f + mod[(size_t)seq * MODW + DM + c + j]));
;                 wv.x = cvt_pk_bf16(h[0], h[1]); wv.y = cvt_pk_bf16(h[2], h[3]); *(u32x2*)(xb + (size_t)r * DM + c) = wv; } } }
.LBB0_119:
	v_ashrrev_i32_e32 v0, 6, v22
	s_lshl_b32 s12, s2, 3
	v_add_u32_e32 v1, s12, v0
	s_mov_b32 s0, 0x8000
	v_cmp_gt_i32_e32 vcc, s0, v1
	v_mbcnt_lo_u32_b32 v17, -1, 0
	s_and_saveexec_b64 s[8:9], vcc
	s_cbranch_execz .LBB0_124
	s_cmpk_lg_u32 s34, 0x100
	s_cbranch_scc1 .Lxp_orig
	v_mbcnt_lo_u32_b32 v20, -1, 0
	v_mbcnt_hi_u32_b32 v20, -1, v20
	v_lshlrev_b32_e32 v21, 3, v20
	v_lshlrev_b32_e32 v20, 4, v20
	v_mov_b32_e32 v23, 0
	v_readlane_b32 s36, v253, 17
	v_readlane_b32 s37, v253, 18
	v_readlane_b32 s38, v253, 19
	v_readlane_b32 s39, v253, 20
	v_readlane_b32 s48, v253, 29
	v_readlane_b32 s49, v253, 30
	s_lshl_b32 s0, s2, 3
	s_add_i32 s0, s0, s33
	s_add_u32 s40, s6, 0x1000
	s_addc_u32 s41, s7, 0
	s_add_u32 s42, s6, 0x7000
	s_addc_u32 s43, s7, 0
	s_add_u32 s44, s6, 0xd000
	s_addc_u32 s45, s7, 0
	global_load_dwordx4 v[104:107], v20, s[48:49] offset:0
	global_load_dwordx4 v[108:111], v20, s[48:49] offset:1024
	global_load_dwordx4 v[112:115], v20, s[48:49] offset:2048
	global_load_dwordx4 v[116:119], v20, s[48:49] offset:3072
	global_load_dwordx4 v[56:59], v20, s[40:41] offset:0
	global_load_dwordx4 v[60:63], v20, s[40:41] offset:1024
	global_load_dwordx4 v[64:67], v20, s[40:41] offset:2048
	global_load_dwordx4 v[68:71], v20, s[40:41] offset:3072
	global_load_dwordx4 v[72:75], v20, s[42:43] offset:0
	global_load_dwordx4 v[76:79], v20, s[42:43] offset:1024
	global_load_dwordx4 v[80:83], v20, s[42:43] offset:2048
	global_load_dwordx4 v[84:87], v20, s[42:43] offset:3072
	global_load_dwordx4 v[88:91], v20, s[44:45] offset:0
	global_load_dwordx4 v[92:95], v20, s[44:45] offset:1024
	global_load_dwordx4 v[96:99], v20, s[44:45] offset:2048
	global_load_dwordx4 v[100:103], v20, s[44:45] offset:3072
	s_lshl_b32 s1, s0, 12
	s_add_u32 s20, s36, s1
	s_addc_u32 s21, s37, 0
	s_add_u32 s14, s30, s4
	s_addc_u32 s15, s31, s5
	s_lshl_b32 s3, s0, 3
	s_add_u32 s16, s14, s3
	s_addc_u32 s17, s15, 0
	s_lshl_b32 s3, s0, 11
	s_add_u32 s14, s14, s3
	s_addc_u32 s15, s15, 0
	s_add_u32 s14, s14, 0x43ec600
	s_addc_u32 s15, s15, 0
	global_load_dwordx4 v[0:3], v20, s[20:21] offset:0
	global_load_dwordx4 v[4:7], v20, s[20:21] offset:1024
	global_load_dwordx4 v[8:11], v20, s[20:21] offset:2048
	global_load_dwordx4 v[12:15], v20, s[20:21] offset:3072
	s_add_u32 s20, s20, 0x800000
	s_addc_u32 s21, s21, 0
	global_load_dwordx4 v[24:27], v20, s[20:21] offset:0
	global_load_dwordx4 v[28:31], v20, s[20:21] offset:1024
	global_load_dwordx4 v[32:35], v20, s[20:21] offset:2048
	global_load_dwordx4 v[36:39], v20, s[20:21] offset:3072
	s_add_u32 s20, s20, 0x800000
	s_addc_u32 s21, s21, 0
	global_load_dwordx4 v[40:43], v20, s[20:21] offset:0
	global_load_dwordx4 v[44:47], v20, s[20:21] offset:1024
	global_load_dwordx4 v[48:51], v20, s[20:21] offset:2048
	global_load_dwordx4 v[52:55], v20, s[20:21] offset:3072
	s_add_u32 s20, s20, 0x800000
	s_addc_u32 s21, s21, 0
	s_waitcnt vmcnt(12)
	v_pk_add_f32 v[56:57], v[56:57], 1.0 op_sel_hi:[1,0]
	v_pk_add_f32 v[58:59], v[58:59], 1.0 op_sel_hi:[1,0]
	v_pk_add_f32 v[60:61], v[60:61], 1.0 op_sel_hi:[1,0]
	v_pk_add_f32 v[62:63], v[62:63], 1.0 op_sel_hi:[1,0]
	v_pk_add_f32 v[64:65], v[64:65], 1.0 op_sel_hi:[1,0]
	v_pk_add_f32 v[66:67], v[66:67], 1.0 op_sel_hi:[1,0]
	v_pk_add_f32 v[68:69], v[68:69], 1.0 op_sel_hi:[1,0]
	v_pk_add_f32 v[70:71], v[70:71], 1.0 op_sel_hi:[1,0]
	v_pk_mul_f32 v[56:57], v[104:105], v[56:57]
	v_pk_mul_f32 v[58:59], v[106:107], v[58:59]
	v_pk_mul_f32 v[60:61], v[108:109], v[60:61]
	v_pk_mul_f32 v[62:63], v[110:111], v[62:63]
	v_pk_mul_f32 v[64:65], v[112:113], v[64:65]
	v_pk_mul_f32 v[66:67], v[114:115], v[66:67]
	v_pk_mul_f32 v[68:69], v[116:117], v[68:69]
	v_pk_mul_f32 v[70:71], v[118:119], v[70:71]
	v_pk_add_f32 v[72:73], v[72:73], 1.0 op_sel_hi:[1,0]
	v_pk_add_f32 v[74:75], v[74:75], 1.0 op_sel_hi:[1,0]
	v_pk_add_f32 v[76:77], v[76:77], 1.0 op_sel_hi:[1,0]
	v_pk_add_f32 v[78:79], v[78:79], 1.0 op_sel_hi:[1,0]
	v_pk_add_f32 v[80:81], v[80:81], 1.0 op_sel_hi:[1,0]
	v_pk_add_f32 v[82:83], v[82:83], 1.0 op_sel_hi:[1,0]
	v_pk_add_f32 v[84:85], v[84:85], 1.0 op_sel_hi:[1,0]
	v_pk_add_f32 v[86:87], v[86:87], 1.0 op_sel_hi:[1,0]
	v_pk_mul_f32 v[72:73], v[104:105], v[72:73]
	v_pk_mul_f32 v[74:75], v[106:107], v[74:75]
	v_pk_mul_f32 v[76:77], v[108:109], v[76:77]
	v_pk_mul_f32 v[78:79], v[110:111], v[78:79]
	v_pk_mul_f32 v[80:81], v[112:113], v[80:81]
	v_pk_mul_f32 v[82:83], v[114:115], v[82:83]
	v_pk_mul_f32 v[84:85], v[116:117], v[84:85]
	v_pk_mul_f32 v[86:87], v[118:119], v[86:87]
	v_pk_add_f32 v[88:89], v[88:89], 1.0 op_sel_hi:[1,0]
	v_pk_add_f32 v[90:91], v[90:91], 1.0 op_sel_hi:[1,0]
	v_pk_add_f32 v[92:93], v[92:93], 1.0 op_sel_hi:[1,0]
	v_pk_add_f32 v[94:95], v[94:95], 1.0 op_sel_hi:[1,0]
	v_pk_add_f32 v[96:97], v[96:97], 1.0 op_sel_hi:[1,0]
	v_pk_add_f32 v[98:99], v[98:99], 1.0 op_sel_hi:[1,0]
	v_pk_add_f32 v[100:101], v[100:101], 1.0 op_sel_hi:[1,0]
	v_pk_add_f32 v[102:103], v[102:103], 1.0 op_sel_hi:[1,0]
	v_pk_mul_f32 v[88:89], v[104:105], v[88:89]
	v_pk_mul_f32 v[90:91], v[106:107], v[90:91]
	v_pk_mul_f32 v[92:93], v[108:109], v[92:93]
	v_pk_mul_f32 v[94:95], v[110:111], v[94:95]
	v_pk_mul_f32 v[96:97], v[112:113], v[96:97]
	v_pk_mul_f32 v[98:99], v[114:115], v[98:99]
	v_pk_mul_f32 v[100:101], v[116:117], v[100:101]
	v_pk_mul_f32 v[102:103], v[118:119], v[102:103]
	global_load_dwordx4 v[104:107], v20, s[20:21] offset:0
	global_load_dwordx4 v[108:111], v20, s[20:21] offset:1024
	global_load_dwordx4 v[112:115], v20, s[20:21] offset:2048
	global_load_dwordx4 v[116:119], v20, s[20:21] offset:3072
	s_add_u32 s20, s20, 0x800000
	s_addc_u32 s21, s21, 0
	s_waitcnt vmcnt(12)
; __device__ __forceinline__ unsigned cvt_pk_bf16(float lo, float hi) { const f2_t v = {lo, hi}; const bf2_t b = __builtin_convertvector(v, bf2_t); return __builtin_bit_cast(unsigned, b); }
; __global__ void __launch_bounds__(NTHR, 2) mega(Params p) {
;     ...
;         for (int r = bid * 8 + wid; r < MTOK; r += G * 8) { const int seq = seq_of_row(r);
;             const float* xr = r < 16384 ? p.xp + (size_t)r * DM : p.xs + (size_t)(r - 16384) * DM; float s = 0.f; f32x4 v[4];
; #pragma unroll
;             for (int jj = 0; jj < 4; ++jj) { v[jj] = *(const f32x4*)(xr + jj * 256 + 4 * lane); s += (v[jj][0] * v[jj][0] + v[jj][1] * v[jj][1]) + (v[jj][2] * v[jj][2] + v[jj][3] * v[jj][3]); }
; #pragma unroll
;             for (int o = 32; o >= 1; o >>= 1) s += __shfl_xor(s, o);
;             if (lane == 0) ssb[r] = (u64)(s * SSK);
; #pragma unroll
;             for (int jj = 0; jj < 4; ++jj) { const int c = jj * 256 + 4 * lane; u32x2 wv; float h[4];
; #pragma unroll
;                 for (int j = 0; j < 4; ++j) h[j] = v[jj][j] * (p.norm_g[c + j] * (1.0f + mod[(size_t)seq * MODW + DM + c + j]));
;                 wv.x = cvt_pk_bf16(h[0], h[1]); wv.y = cvt_pk_bf16(h[2], h[3]); *(u32x2*)(xb + (size_t)r * DM + c) = wv; } } }
	v_mul_f32_e32 v16, v0, v0
	v_mul_f32_e32 v18, v1, v1
	v_fmac_f32_e32 v16, v2, v2
	v_fmac_f32_e32 v18, v3, v3
	v_fmac_f32_e32 v16, v4, v4
	v_fmac_f32_e32 v18, v5, v5
	v_fmac_f32_e32 v16, v6, v6
	v_fmac_f32_e32 v18, v7, v7
	v_fmac_f32_e32 v16, v8, v8
	v_fmac_f32_e32 v18, v9, v9
	v_fmac_f32_e32 v16, v10, v10
	v_fmac_f32_e32 v18, v11, v11
	v_fmac_f32_e32 v16, v12, v12
	v_fmac_f32_e32 v18, v13, v13
	v_fmac_f32_e32 v16, v14, v14
	v_fmac_f32_e32 v18, v15, v15
	v_add_f32_e32 v16, v16, v18
	v_pk_mul_f32 v[0:1], v[0:1], v[56:57]
	v_pk_mul_f32 v[2:3], v[2:3], v[58:59]
	v_pk_mul_f32 v[4:5], v[4:5], v[60:61]
	v_pk_mul_f32 v[6:7], v[6:7], v[62:63]
	v_add_f32_dpp v16, v16, v16 quad_perm:[1,0,3,2] row_mask:0xf bank_mask:0xf
	v_pk_mul_f32 v[8:9], v[8:9], v[64:65]
	v_pk_mul_f32 v[10:11], v[10:11], v[66:67]
	v_pk_mul_f32 v[12:13], v[12:13], v[68:69]
	v_pk_mul_f32 v[14:15], v[14:15], v[70:71]
	v_add_f32_dpp v16, v16, v16 quad_perm:[2,3,0,1] row_mask:0xf bank_mask:0xf
	v_cvt_pk_bf16_f32 v0, v0, v1
	v_cvt_pk_bf16_f32 v1, v2, v3
	v_cvt_pk_bf16_f32 v4, v4, v5
	v_cvt_pk_bf16_f32 v5, v6, v7
	v_add_f32_dpp v16, v16, v16 row_ror:4 row_mask:0xf bank_mask:0xf
	v_cvt_pk_bf16_f32 v8, v8, v9
	v_cvt_pk_bf16_f32 v9, v10, v11
	v_cvt_pk_bf16_f32 v12, v12, v13
	v_cvt_pk_bf16_f32 v13, v14, v15
	v_add_f32_dpp v16, v16, v16 row_ror:8 row_mask:0xf bank_mask:0xf
	global_store_dwordx2 v21, v[0:1], s[14:15] offset:0
	global_store_dwordx2 v21, v[4:5], s[14:15] offset:512
	global_store_dwordx2 v21, v[8:9], s[14:15] offset:1024
	global_store_dwordx2 v21, v[12:13], s[14:15] offset:1536
	v_readlane_b32 s0, v16, 0
	v_readlane_b32 s3, v16, 16
	v_readlane_b32 s10, v16, 32
	v_readlane_b32 s11, v16, 48
	v_mov_b32_e32 v18, s0
	v_add_f32_e32 v18, s3, v18
	v_add_f32_e32 v18, s10, v18
	v_add_f32_e32 v18, s11, v18
	v_mul_f32_e32 v18, 0x49800000, v18
	v_trunc_f32_e32 v18, v18
	v_mul_f32_e32 v19, 0x2f800000, v18
	v_floor_f32_e32 v19, v19
	v_fmac_f32_e32 v18, 0xcf800000, v19
	v_cvt_u32_f32_e32 v18, v18
	v_cvt_u32_f32_e32 v19, v19
	s_mov_b64 exec, 1
	global_store_dwordx2 v23, v[18:19], s[16:17]
	s_mov_b64 exec, -1
	s_add_u32 s14, s14, 0x400000
	s_addc_u32 s15, s15, 0
	s_add_u32 s16, s16, 0x4000
	s_addc_u32 s17, s17, 0
	global_load_dwordx4 v[0:3], v20, s[20:21] offset:0
	global_load_dwordx4 v[4:7], v20, s[20:21] offset:1024
	global_load_dwordx4 v[8:11], v20, s[20:21] offset:2048
	global_load_dwordx4 v[12:15], v20, s[20:21] offset:3072
	s_add_u32 s20, s20, 0x800000
	s_addc_u32 s21, s21, 0
	s_waitcnt vmcnt(17)
	v_mul_f32_e32 v16, v24, v24
	v_mul_f32_e32 v18, v25, v25
	v_fmac_f32_e32 v16, v26, v26
	v_fmac_f32_e32 v18, v27, v27
	v_fmac_f32_e32 v16, v28, v28
	v_fmac_f32_e32 v18, v29, v29
	v_fmac_f32_e32 v16, v30, v30
	v_fmac_f32_e32 v18, v31, v31
	v_fmac_f32_e32 v16, v32, v32
	v_fmac_f32_e32 v18, v33, v33
	v_fmac_f32_e32 v16, v34, v34
	v_fmac_f32_e32 v18, v35, v35
	v_fmac_f32_e32 v16, v36, v36
	v_fmac_f32_e32 v18, v37, v37
	v_fmac_f32_e32 v16, v38, v38
	v_fmac_f32_e32 v18, v39, v39
	v_add_f32_e32 v16, v16, v18
	v_pk_mul_f32 v[24:25], v[24:25], v[56:57]
	v_pk_mul_f32 v[26:27], v[26:27], v[58:59]
	v_pk_mul_f32 v[28:29], v[28:29], v[60:61]
	v_pk_mul_f32 v[30:31], v[30:31], v[62:63]
	v_add_f32_dpp v16, v16, v16 quad_perm:[1,0,3,2] row_mask:0xf bank_mask:0xf
	v_pk_mul_f32 v[32:33], v[32:33], v[64:65]
	v_pk_mul_f32 v[34:35], v[34:35], v[66:67]
	v_pk_mul_f32 v[36:37], v[36:37], v[68:69]
	v_pk_mul_f32 v[38:39], v[38:39], v[70:71]
	v_add_f32_dpp v16, v16, v16 quad_perm:[2,3,0,1] row_mask:0xf bank_mask:0xf
	v_cvt_pk_bf16_f32 v24, v24, v25
	v_cvt_pk_bf16_f32 v25, v26, v27
	v_cvt_pk_bf16_f32 v28, v28, v29
	v_cvt_pk_bf16_f32 v29, v30, v31
	v_add_f32_dpp v16, v16, v16 row_ror:4 row_mask:0xf bank_mask:0xf
	v_cvt_pk_bf16_f32 v32, v32, v33
	v_cvt_pk_bf16_f32 v33, v34, v35
	v_cvt_pk_bf16_f32 v36, v36, v37
	v_cvt_pk_bf16_f32 v37, v38, v39
	v_add_f32_dpp v16, v16, v16 row_ror:8 row_mask:0xf bank_mask:0xf
	global_store_dwordx2 v21, v[24:25], s[14:15] offset:0
	global_store_dwordx2 v21, v[28:29], s[14:15] offset:512
	global_store_dwordx2 v21, v[32:33], s[14:15] offset:1024
	global_store_dwordx2 v21, v[36:37], s[14:15] offset:1536
	v_readlane_b32 s0, v16, 0
	v_readlane_b32 s3, v16, 16
	v_readlane_b32 s10, v16, 32
	v_readlane_b32 s11, v16, 48
	v_mov_b32_e32 v18, s0
	v_add_f32_e32 v18, s3, v18
	v_add_f32_e32 v18, s10, v18
	v_add_f32_e32 v18, s11, v18
	v_mul_f32_e32 v18, 0x49800000, v18
	v_trunc_f32_e32 v18, v18
	v_mul_f32_e32 v19, 0x2f800000, v18
	v_floor_f32_e32 v19, v19
	v_fmac_f32_e32 v18, 0xcf800000, v19
	v_cvt_u32_f32_e32 v18, v18
	v_cvt_u32_f32_e32 v19, v19
	s_mov_b64 exec, 1
	global_store_dwordx2 v23, v[18:19], s[16:17]
	s_mov_b64 exec, -1
	s_add_u32 s14, s14, 0x400000
	s_addc_u32 s15, s15, 0
	s_add_u32 s16, s16, 0x4000
	s_addc_u32 s17, s17, 0
	global_load_dwordx4 v[24:27], v20, s[20:21] offset:0
	global_load_dwordx4 v[28:31], v20, s[20:21] offset:1024
	global_load_dwordx4 v[32:35], v20, s[20:21] offset:2048
	global_load_dwordx4 v[36:39], v20, s[20:21] offset:3072
	s_add_u32 s20, s20, 0x800000
	s_addc_u32 s21, s21, 0
	s_waitcnt vmcnt(22)
; __device__ __forceinline__ unsigned cvt_pk_bf16(float lo, float hi) { const f2_t v = {lo, hi}; const bf2_t b = __builtin_convertvector(v, bf2_t); return __builtin_bit_cast(unsigned, b); }
; __global__ void __launch_bounds__(NTHR, 2) mega(Params p) {
;     ...
;         for (int r = bid * 8 + wid; r < MTOK; r += G * 8) { const int seq = seq_of_row(r);
;             const float* xr = r < 16384 ? p.xp + (size_t)r * DM : p.xs + (size_t)(r - 16384) * DM; float s = 0.f; f32x4 v[4];
; #pragma unroll
;             for (int jj = 0; jj < 4; ++jj) { v[jj] = *(const f32x4*)(xr + jj * 256 + 4 * lane); s += (v[jj][0] * v[jj][0] + v[jj][1] * v[jj][1]) + (v[jj][2] * v[jj][2] + v[jj][3] * v[jj][3]); }
; #pragma unroll
;             for (int o = 32; o >= 1; o >>= 1) s += __shfl_xor(s, o);
;             if (lane == 0) ssb[r] = (u64)(s * SSK);
; #pragma unroll
;             for (int jj = 0; jj < 4; ++jj) { const int c = jj * 256 + 4 * lane; u32x2 wv; float h[4];
; #pragma unroll
;                 for (int j = 0; j < 4; ++j) h[j] = v[jj][j] * (p.norm_g[c + j] * (1.0f + mod[(size_t)seq * MODW + DM + c + j]));
;                 wv.x = cvt_pk_bf16(h[0], h[1]); wv.y = cvt_pk_bf16(h[2], h[3]); *(u32x2*)(xb + (size_t)r * DM + c) = wv; } } }
	v_mul_f32_e32 v16, v40, v40
	v_mul_f32_e32 v18, v41, v41
	v_fmac_f32_e32 v16, v42, v42
	v_fmac_f32_e32 v18, v43, v43
	v_fmac_f32_e32 v16, v44, v44
	v_fmac_f32_e32 v18, v45, v45
	v_fmac_f32_e32 v16, v46, v46
	v_fmac_f32_e32 v18, v47, v47
	v_fmac_f32_e32 v16, v48, v48
	v_fmac_f32_e32 v18, v49, v49
	v_fmac_f32_e32 v16, v50, v50
	v_fmac_f32_e32 v18, v51, v51
	v_fmac_f32_e32 v16, v52, v52
	v_fmac_f32_e32 v18, v53, v53
	v_fmac_f32_e32 v16, v54, v54
	v_fmac_f32_e32 v18, v55, v55
	v_add_f32_e32 v16, v16, v18
	v_pk_mul_f32 v[40:41], v[40:41], v[56:57]
	v_pk_mul_f32 v[42:43], v[42:43], v[58:59]
	v_pk_mul_f32 v[44:45], v[44:45], v[60:61]
	v_pk_mul_f32 v[46:47], v[46:47], v[62:63]
	v_add_f32_dpp v16, v16, v16 quad_perm:[1,0,3,2] row_mask:0xf bank_mask:0xf
	v_pk_mul_f32 v[48:49], v[48:49], v[64:65]
	v_pk_mul_f32 v[50:51], v[50:51], v[66:67]
	v_pk_mul_f32 v[52:53], v[52:53], v[68:69]
	v_pk_mul_f32 v[54:55], v[54:55], v[70:71]
	v_add_f32_dpp v16, v16, v16 quad_perm:[2,3,0,1] row_mask:0xf bank_mask:0xf
	v_cvt_pk_bf16_f32 v40, v40, v41
	v_cvt_pk_bf16_f32 v41, v42, v43
	v_cvt_pk_bf16_f32 v44, v44, v45
	v_cvt_pk_bf16_f32 v45, v46, v47
	v_add_f32_dpp v16, v16, v16 row_ror:4 row_mask:0xf bank_mask:0xf
	v_cvt_pk_bf16_f32 v48, v48, v49
	v_cvt_pk_bf16_f32 v49, v50, v51
	v_cvt_pk_bf16_f32 v52, v52, v53
	v_cvt_pk_bf16_f32 v53, v54, v55
	v_add_f32_dpp v16, v16, v16 row_ror:8 row_mask:0xf bank_mask:0xf
	global_store_dwordx2 v21, v[40:41], s[14:15] offset:0
	global_store_dwordx2 v21, v[44:45], s[14:15] offset:512
	global_store_dwordx2 v21, v[48:49], s[14:15] offset:1024
	global_store_dwordx2 v21, v[52:53], s[14:15] offset:1536
	v_readlane_b32 s0, v16, 0
	v_readlane_b32 s3, v16, 16
	v_readlane_b32 s10, v16, 32
	v_readlane_b32 s11, v16, 48
	v_mov_b32_e32 v18, s0
	v_add_f32_e32 v18, s3, v18
	v_add_f32_e32 v18, s10, v18
	v_add_f32_e32 v18, s11, v18
	v_mul_f32_e32 v18, 0x49800000, v18
	v_trunc_f32_e32 v18, v18
	v_mul_f32_e32 v19, 0x2f800000, v18
	v_floor_f32_e32 v19, v19
	v_fmac_f32_e32 v18, 0xcf800000, v19
	v_cvt_u32_f32_e32 v18, v18
	v_cvt_u32_f32_e32 v19, v19
	s_mov_b64 exec, 1
	global_store_dwordx2 v23, v[18:19], s[16:17]
	s_mov_b64 exec, -1
	s_add_u32 s14, s14, 0x400000
	s_addc_u32 s15, s15, 0
	s_add_u32 s16, s16, 0x4000
	s_addc_u32 s17, s17, 0
	global_load_dwordx4 v[40:43], v20, s[20:21] offset:0
	global_load_dwordx4 v[44:47], v20, s[20:21] offset:1024
	global_load_dwordx4 v[48:51], v20, s[20:21] offset:2048
	global_load_dwordx4 v[52:55], v20, s[20:21] offset:3072
	s_add_u32 s20, s20, 0x800000
	s_addc_u32 s21, s21, 0
	s_waitcnt vmcnt(27)
	v_mul_f32_e32 v16, v104, v104
	v_mul_f32_e32 v18, v105, v105
	v_fmac_f32_e32 v16, v106, v106
	v_fmac_f32_e32 v18, v107, v107
	v_fmac_f32_e32 v16, v108, v108
	v_fmac_f32_e32 v18, v109, v109
	v_fmac_f32_e32 v16, v110, v110
	v_fmac_f32_e32 v18, v111, v111
	v_fmac_f32_e32 v16, v112, v112
	v_fmac_f32_e32 v18, v113, v113
	v_fmac_f32_e32 v16, v114, v114
	v_fmac_f32_e32 v18, v115, v115
	v_fmac_f32_e32 v16, v116, v116
	v_fmac_f32_e32 v18, v117, v117
	v_fmac_f32_e32 v16, v118, v118
	v_fmac_f32_e32 v18, v119, v119
	v_add_f32_e32 v16, v16, v18
	v_pk_mul_f32 v[104:105], v[104:105], v[56:57]
	v_pk_mul_f32 v[106:107], v[106:107], v[58:59]
	v_pk_mul_f32 v[108:109], v[108:109], v[60:61]
	v_pk_mul_f32 v[110:111], v[110:111], v[62:63]
	v_add_f32_dpp v16, v16, v16 quad_perm:[1,0,3,2] row_mask:0xf bank_mask:0xf
	v_pk_mul_f32 v[112:113], v[112:113], v[64:65]
	v_pk_mul_f32 v[114:115], v[114:115], v[66:67]
	v_pk_mul_f32 v[116:117], v[116:117], v[68:69]
	v_pk_mul_f32 v[118:119], v[118:119], v[70:71]
	v_add_f32_dpp v16, v16, v16 quad_perm:[2,3,0,1] row_mask:0xf bank_mask:0xf
	v_cvt_pk_bf16_f32 v104, v104, v105
	v_cvt_pk_bf16_f32 v105, v106, v107
	v_cvt_pk_bf16_f32 v108, v108, v109
	v_cvt_pk_bf16_f32 v109, v110, v111
	v_add_f32_dpp v16, v16, v16 row_ror:4 row_mask:0xf bank_mask:0xf
	v_cvt_pk_bf16_f32 v112, v112, v113
	v_cvt_pk_bf16_f32 v113, v114, v115
	v_cvt_pk_bf16_f32 v116, v116, v117
	v_cvt_pk_bf16_f32 v117, v118, v119
	v_add_f32_dpp v16, v16, v16 row_ror:8 row_mask:0xf bank_mask:0xf
	global_store_dwordx2 v21, v[104:105], s[14:15] offset:0
	global_store_dwordx2 v21, v[108:109], s[14:15] offset:512
	global_store_dwordx2 v21, v[112:113], s[14:15] offset:1024
	global_store_dwordx2 v21, v[116:117], s[14:15] offset:1536
	v_readlane_b32 s0, v16, 0
	v_readlane_b32 s3, v16, 16
	v_readlane_b32 s10, v16, 32
	v_readlane_b32 s11, v16, 48
	v_mov_b32_e32 v18, s0
	v_add_f32_e32 v18, s3, v18
	v_add_f32_e32 v18, s10, v18
	v_add_f32_e32 v18, s11, v18
	v_mul_f32_e32 v18, 0x49800000, v18
	v_trunc_f32_e32 v18, v18
	v_mul_f32_e32 v19, 0x2f800000, v18
	v_floor_f32_e32 v19, v19
	v_fmac_f32_e32 v18, 0xcf800000, v19
	v_cvt_u32_f32_e32 v18, v18
	v_cvt_u32_f32_e32 v19, v19
	s_mov_b64 exec, 1
	global_store_dwordx2 v23, v[18:19], s[16:17]
	s_mov_b64 exec, -1
	s_add_u32 s14, s14, 0x400000
	s_addc_u32 s15, s15, 0
	s_add_u32 s16, s16, 0x4000
	s_addc_u32 s17, s17, 0
	global_load_dwordx4 v[104:107], v20, s[20:21] offset:0
	global_load_dwordx4 v[108:111], v20, s[20:21] offset:1024
	global_load_dwordx4 v[112:115], v20, s[20:21] offset:2048
	global_load_dwordx4 v[116:119], v20, s[20:21] offset:3072
	s_waitcnt vmcnt(27)
; __device__ __forceinline__ unsigned cvt_pk_bf16(float lo, float hi) { const f2_t v = {lo, hi}; const bf2_t b = __builtin_convertvector(v, bf2_t); return __builtin_bit_cast(unsigned, b); }
; __global__ void __launch_bounds__(NTHR, 2) mega(Params p) {
;     ...
;         for (int r = bid * 8 + wid; r < MTOK; r += G * 8) { const int seq = seq_of_row(r);
;             const float* xr = r < 16384 ? p.xp + (size_t)r * DM : p.xs + (size_t)(r - 16384) * DM; float s = 0.f; f32x4 v[4];
; #pragma unroll
;             for (int jj = 0; jj < 4; ++jj) { v[jj] = *(const f32x4*)(xr + jj * 256 + 4 * lane); s += (v[jj][0] * v[jj][0] + v[jj][1] * v[jj][1]) + (v[jj][2] * v[jj][2] + v[jj][3] * v[jj][3]); }
; #pragma unroll
;             for (int o = 32; o >= 1; o >>= 1) s += __shfl_xor(s, o);
;             if (lane == 0) ssb[r] = (u64)(s * SSK);
; #pragma unroll
;             for (int jj = 0; jj < 4; ++jj) { const int c = jj * 256 + 4 * lane; u32x2 wv; float h[4];
; #pragma unroll
;                 for (int j = 0; j < 4; ++j) h[j] = v[jj][j] * (p.norm_g[c + j] * (1.0f + mod[(size_t)seq * MODW + DM + c + j]));
;                 wv.x = cvt_pk_bf16(h[0], h[1]); wv.y = cvt_pk_bf16(h[2], h[3]); *(u32x2*)(xb + (size_t)r * DM + c) = wv; } } }
	v_mul_f32_e32 v16, v0, v0
	v_mul_f32_e32 v18, v1, v1
	v_fmac_f32_e32 v16, v2, v2
	v_fmac_f32_e32 v18, v3, v3
	v_fmac_f32_e32 v16, v4, v4
	v_fmac_f32_e32 v18, v5, v5
	v_fmac_f32_e32 v16, v6, v6
	v_fmac_f32_e32 v18, v7, v7
	v_fmac_f32_e32 v16, v8, v8
	v_fmac_f32_e32 v18, v9, v9
	v_fmac_f32_e32 v16, v10, v10
	v_fmac_f32_e32 v18, v11, v11
	v_fmac_f32_e32 v16, v12, v12
	v_fmac_f32_e32 v18, v13, v13
	v_fmac_f32_e32 v16, v14, v14
	v_fmac_f32_e32 v18, v15, v15
	v_add_f32_e32 v16, v16, v18
	v_pk_mul_f32 v[0:1], v[0:1], v[72:73]
	v_pk_mul_f32 v[2:3], v[2:3], v[74:75]
	v_pk_mul_f32 v[4:5], v[4:5], v[76:77]
	v_pk_mul_f32 v[6:7], v[6:7], v[78:79]
	v_add_f32_dpp v16, v16, v16 quad_perm:[1,0,3,2] row_mask:0xf bank_mask:0xf
	v_pk_mul_f32 v[8:9], v[8:9], v[80:81]
	v_pk_mul_f32 v[10:11], v[10:11], v[82:83]
	v_pk_mul_f32 v[12:13], v[12:13], v[84:85]
	v_pk_mul_f32 v[14:15], v[14:15], v[86:87]
	v_add_f32_dpp v16, v16, v16 quad_perm:[2,3,0,1] row_mask:0xf bank_mask:0xf
	v_cvt_pk_bf16_f32 v0, v0, v1
	v_cvt_pk_bf16_f32 v1, v2, v3
	v_cvt_pk_bf16_f32 v4, v4, v5
	v_cvt_pk_bf16_f32 v5, v6, v7
	v_add_f32_dpp v16, v16, v16 row_ror:4 row_mask:0xf bank_mask:0xf
	v_cvt_pk_bf16_f32 v8, v8, v9
	v_cvt_pk_bf16_f32 v9, v10, v11
	v_cvt_pk_bf16_f32 v12, v12, v13
	v_cvt_pk_bf16_f32 v13, v14, v15
	v_add_f32_dpp v16, v16, v16 row_ror:8 row_mask:0xf bank_mask:0xf
	global_store_dwordx2 v21, v[0:1], s[14:15] offset:0
	global_store_dwordx2 v21, v[4:5], s[14:15] offset:512
	global_store_dwordx2 v21, v[8:9], s[14:15] offset:1024
	global_store_dwordx2 v21, v[12:13], s[14:15] offset:1536
	v_readlane_b32 s0, v16, 0
	v_readlane_b32 s3, v16, 16
	v_readlane_b32 s10, v16, 32
	v_readlane_b32 s11, v16, 48
	v_mov_b32_e32 v18, s0
	v_add_f32_e32 v18, s3, v18
	v_add_f32_e32 v18, s10, v18
	v_add_f32_e32 v18, s11, v18
	v_mul_f32_e32 v18, 0x49800000, v18
	v_trunc_f32_e32 v18, v18
	v_mul_f32_e32 v19, 0x2f800000, v18
	v_floor_f32_e32 v19, v19
	v_fmac_f32_e32 v18, 0xcf800000, v19
	v_cvt_u32_f32_e32 v18, v18
	v_cvt_u32_f32_e32 v19, v19
	s_mov_b64 exec, 1
	global_store_dwordx2 v23, v[18:19], s[16:17]
	s_mov_b64 exec, -1
	s_add_u32 s14, s14, 0x400000
	s_addc_u32 s15, s15, 0
	s_add_u32 s16, s16, 0x4000
	s_addc_u32 s17, s17, 0
	s_add_u32 s20, s38, s1
	s_addc_u32 s21, s39, 0
	global_load_dwordx4 v[0:3], v20, s[20:21] offset:0
	global_load_dwordx4 v[4:7], v20, s[20:21] offset:1024
	global_load_dwordx4 v[8:11], v20, s[20:21] offset:2048
	global_load_dwordx4 v[12:15], v20, s[20:21] offset:3072
	s_add_u32 s20, s20, 0x800000
	s_addc_u32 s21, s21, 0
	s_waitcnt vmcnt(27)
	v_mul_f32_e32 v16, v24, v24
	v_mul_f32_e32 v18, v25, v25
	v_fmac_f32_e32 v16, v26, v26
	v_fmac_f32_e32 v18, v27, v27
	v_fmac_f32_e32 v16, v28, v28
	v_fmac_f32_e32 v18, v29, v29
	v_fmac_f32_e32 v16, v30, v30
	v_fmac_f32_e32 v18, v31, v31
	v_fmac_f32_e32 v16, v32, v32
	v_fmac_f32_e32 v18, v33, v33
	v_fmac_f32_e32 v16, v34, v34
	v_fmac_f32_e32 v18, v35, v35
	v_fmac_f32_e32 v16, v36, v36
	v_fmac_f32_e32 v18, v37, v37
	v_fmac_f32_e32 v16, v38, v38
	v_fmac_f32_e32 v18, v39, v39
	v_add_f32_e32 v16, v16, v18
	v_pk_mul_f32 v[24:25], v[24:25], v[72:73]
	v_pk_mul_f32 v[26:27], v[26:27], v[74:75]
	v_pk_mul_f32 v[28:29], v[28:29], v[76:77]
	v_pk_mul_f32 v[30:31], v[30:31], v[78:79]
	v_add_f32_dpp v16, v16, v16 quad_perm:[1,0,3,2] row_mask:0xf bank_mask:0xf
	v_pk_mul_f32 v[32:33], v[32:33], v[80:81]
	v_pk_mul_f32 v[34:35], v[34:35], v[82:83]
	v_pk_mul_f32 v[36:37], v[36:37], v[84:85]
	v_pk_mul_f32 v[38:39], v[38:39], v[86:87]
	v_add_f32_dpp v16, v16, v16 quad_perm:[2,3,0,1] row_mask:0xf bank_mask:0xf
	v_cvt_pk_bf16_f32 v24, v24, v25
	v_cvt_pk_bf16_f32 v25, v26, v27
	v_cvt_pk_bf16_f32 v28, v28, v29
	v_cvt_pk_bf16_f32 v29, v30, v31
	v_add_f32_dpp v16, v16, v16 row_ror:4 row_mask:0xf bank_mask:0xf
	v_cvt_pk_bf16_f32 v32, v32, v33
	v_cvt_pk_bf16_f32 v33, v34, v35
	v_cvt_pk_bf16_f32 v36, v36, v37
	v_cvt_pk_bf16_f32 v37, v38, v39
	v_add_f32_dpp v16, v16, v16 row_ror:8 row_mask:0xf bank_mask:0xf
	global_store_dwordx2 v21, v[24:25], s[14:15] offset:0
	global_store_dwordx2 v21, v[28:29], s[14:15] offset:512
	global_store_dwordx2 v21, v[32:33], s[14:15] offset:1024
	global_store_dwordx2 v21, v[36:37], s[14:15] offset:1536
	v_readlane_b32 s0, v16, 0
	v_readlane_b32 s3, v16, 16
	v_readlane_b32 s10, v16, 32
	v_readlane_b32 s11, v16, 48
	v_mov_b32_e32 v18, s0
	v_add_f32_e32 v18, s3, v18
	v_add_f32_e32 v18, s10, v18
	v_add_f32_e32 v18, s11, v18
	v_mul_f32_e32 v18, 0x49800000, v18
	v_trunc_f32_e32 v18, v18
	v_mul_f32_e32 v19, 0x2f800000, v18
	v_floor_f32_e32 v19, v19
	v_fmac_f32_e32 v18, 0xcf800000, v19
	v_cvt_u32_f32_e32 v18, v18
	v_cvt_u32_f32_e32 v19, v19
	s_mov_b64 exec, 1
	global_store_dwordx2 v23, v[18:19], s[16:17]
	s_mov_b64 exec, -1
	s_add_u32 s14, s14, 0x400000
	s_addc_u32 s15, s15, 0
	s_add_u32 s16, s16, 0x4000
	s_addc_u32 s17, s17, 0
	global_load_dwordx4 v[24:27], v20, s[20:21] offset:0
	global_load_dwordx4 v[28:31], v20, s[20:21] offset:1024
	global_load_dwordx4 v[32:35], v20, s[20:21] offset:2048
	global_load_dwordx4 v[36:39], v20, s[20:21] offset:3072
	s_add_u32 s20, s20, 0x800000
	s_addc_u32 s21, s21, 0
	s_waitcnt vmcnt(27)
; __device__ __forceinline__ unsigned cvt_pk_bf16(float lo, float hi) { const f2_t v = {lo, hi}; const bf2_t b = __builtin_convertvector(v, bf2_t); return __builtin_bit_cast(unsigned, b); }
; __global__ void __launch_bounds__(NTHR, 2) mega(Params p) {
;     ...
;         for (int r = bid * 8 + wid; r < MTOK; r += G * 8) { const int seq = seq_of_row(r);
;             const float* xr = r < 16384 ? p.xp + (size_t)r * DM : p.xs + (size_t)(r - 16384) * DM; float s = 0.f; f32x4 v[4];
; #pragma unroll
;             for (int jj = 0; jj < 4; ++jj) { v[jj] = *(const f32x4*)(xr + jj * 256 + 4 * lane); s += (v[jj][0] * v[jj][0] + v[jj][1] * v[jj][1]) + (v[jj][2] * v[jj][2] + v[jj][3] * v[jj][3]); }
; #pragma unroll
;             for (int o = 32; o >= 1; o >>= 1) s += __shfl_xor(s, o);
;             if (lane == 0) ssb[r] = (u64)(s * SSK);
; #pragma unroll
;             for (int jj = 0; jj < 4; ++jj) { const int c = jj * 256 + 4 * lane; u32x2 wv; float h[4];
; #pragma unroll
;                 for (int j = 0; j < 4; ++j) h[j] = v[jj][j] * (p.norm_g[c + j] * (1.0f + mod[(size_t)seq * MODW + DM + c + j]));
;                 wv.x = cvt_pk_bf16(h[0], h[1]); wv.y = cvt_pk_bf16(h[2], h[3]); *(u32x2*)(xb + (size_t)r * DM + c) = wv; } } }
	v_mul_f32_e32 v16, v40, v40
	v_mul_f32_e32 v18, v41, v41
	v_fmac_f32_e32 v16, v42, v42
	v_fmac_f32_e32 v18, v43, v43
	v_fmac_f32_e32 v16, v44, v44
	v_fmac_f32_e32 v18, v45, v45
	v_fmac_f32_e32 v16, v46, v46
	v_fmac_f32_e32 v18, v47, v47
	v_fmac_f32_e32 v16, v48, v48
	v_fmac_f32_e32 v18, v49, v49
	v_fmac_f32_e32 v16, v50, v50
	v_fmac_f32_e32 v18, v51, v51
	v_fmac_f32_e32 v16, v52, v52
	v_fmac_f32_e32 v18, v53, v53
	v_fmac_f32_e32 v16, v54, v54
	v_fmac_f32_e32 v18, v55, v55
	v_add_f32_e32 v16, v16, v18
	v_pk_mul_f32 v[40:41], v[40:41], v[72:73]
	v_pk_mul_f32 v[42:43], v[42:43], v[74:75]
	v_pk_mul_f32 v[44:45], v[44:45], v[76:77]
	v_pk_mul_f32 v[46:47], v[46:47], v[78:79]
	v_add_f32_dpp v16, v16, v16 quad_perm:[1,0,3,2] row_mask:0xf bank_mask:0xf
	v_pk_mul_f32 v[48:49], v[48:49], v[80:81]
	v_pk_mul_f32 v[50:51], v[50:51], v[82:83]
	v_pk_mul_f32 v[52:53], v[52:53], v[84:85]
	v_pk_mul_f32 v[54:55], v[54:55], v[86:87]
	v_add_f32_dpp v16, v16, v16 quad_perm:[2,3,0,1] row_mask:0xf bank_mask:0xf
	v_cvt_pk_bf16_f32 v40, v40, v41
	v_cvt_pk_bf16_f32 v41, v42, v43
	v_cvt_pk_bf16_f32 v44, v44, v45
	v_cvt_pk_bf16_f32 v45, v46, v47
	v_add_f32_dpp v16, v16, v16 row_ror:4 row_mask:0xf bank_mask:0xf
	v_cvt_pk_bf16_f32 v48, v48, v49
	v_cvt_pk_bf16_f32 v49, v50, v51
	v_cvt_pk_bf16_f32 v52, v52, v53
	v_cvt_pk_bf16_f32 v53, v54, v55
	v_add_f32_dpp v16, v16, v16 row_ror:8 row_mask:0xf bank_mask:0xf
	global_store_dwordx2 v21, v[40:41], s[14:15] offset:0
	global_store_dwordx2 v21, v[44:45], s[14:15] offset:512
	global_store_dwordx2 v21, v[48:49], s[14:15] offset:1024
	global_store_dwordx2 v21, v[52:53], s[14:15] offset:1536
	v_readlane_b32 s0, v16, 0
	v_readlane_b32 s3, v16, 16
	v_readlane_b32 s10, v16, 32
	v_readlane_b32 s11, v16, 48
	v_mov_b32_e32 v18, s0
	v_add_f32_e32 v18, s3, v18
	v_add_f32_e32 v18, s10, v18
	v_add_f32_e32 v18, s11, v18
	v_mul_f32_e32 v18, 0x49800000, v18
	v_trunc_f32_e32 v18, v18
	v_mul_f32_e32 v19, 0x2f800000, v18
	v_floor_f32_e32 v19, v19
	v_fmac_f32_e32 v18, 0xcf800000, v19
	v_cvt_u32_f32_e32 v18, v18
	v_cvt_u32_f32_e32 v19, v19
	s_mov_b64 exec, 1
	global_store_dwordx2 v23, v[18:19], s[16:17]
	s_mov_b64 exec, -1
	s_add_u32 s14, s14, 0x400000
	s_addc_u32 s15, s15, 0
	s_add_u32 s16, s16, 0x4000
	s_addc_u32 s17, s17, 0
	global_load_dwordx4 v[40:43], v20, s[20:21] offset:0
	global_load_dwordx4 v[44:47], v20, s[20:21] offset:1024
	global_load_dwordx4 v[48:51], v20, s[20:21] offset:2048
	global_load_dwordx4 v[52:55], v20, s[20:21] offset:3072
	s_add_u32 s20, s20, 0x800000
	s_addc_u32 s21, s21, 0
	s_waitcnt vmcnt(27)
	v_mul_f32_e32 v16, v104, v104
	v_mul_f32_e32 v18, v105, v105
	v_fmac_f32_e32 v16, v106, v106
	v_fmac_f32_e32 v18, v107, v107
	v_fmac_f32_e32 v16, v108, v108
	v_fmac_f32_e32 v18, v109, v109
	v_fmac_f32_e32 v16, v110, v110
	v_fmac_f32_e32 v18, v111, v111
	v_fmac_f32_e32 v16, v112, v112
	v_fmac_f32_e32 v18, v113, v113
	v_fmac_f32_e32 v16, v114, v114
	v_fmac_f32_e32 v18, v115, v115
	v_fmac_f32_e32 v16, v116, v116
	v_fmac_f32_e32 v18, v117, v117
	v_fmac_f32_e32 v16, v118, v118
	v_fmac_f32_e32 v18, v119, v119
	v_add_f32_e32 v16, v16, v18
	v_pk_mul_f32 v[104:105], v[104:105], v[72:73]
	v_pk_mul_f32 v[106:107], v[106:107], v[74:75]
	v_pk_mul_f32 v[108:109], v[108:109], v[76:77]
	v_pk_mul_f32 v[110:111], v[110:111], v[78:79]
	v_add_f32_dpp v16, v16, v16 quad_perm:[1,0,3,2] row_mask:0xf bank_mask:0xf
	v_pk_mul_f32 v[112:113], v[112:113], v[80:81]
	v_pk_mul_f32 v[114:115], v[114:115], v[82:83]
	v_pk_mul_f32 v[116:117], v[116:117], v[84:85]
	v_pk_mul_f32 v[118:119], v[118:119], v[86:87]
	v_add_f32_dpp v16, v16, v16 quad_perm:[2,3,0,1] row_mask:0xf bank_mask:0xf
	v_cvt_pk_bf16_f32 v104, v104, v105
	v_cvt_pk_bf16_f32 v105, v106, v107
	v_cvt_pk_bf16_f32 v108, v108, v109
	v_cvt_pk_bf16_f32 v109, v110, v111
	v_add_f32_dpp v16, v16, v16 row_ror:4 row_mask:0xf bank_mask:0xf
	v_cvt_pk_bf16_f32 v112, v112, v113
	v_cvt_pk_bf16_f32 v113, v114, v115
	v_cvt_pk_bf16_f32 v116, v116, v117
	v_cvt_pk_bf16_f32 v117, v118, v119
	v_add_f32_dpp v16, v16, v16 row_ror:8 row_mask:0xf bank_mask:0xf
	global_store_dwordx2 v21, v[104:105], s[14:15] offset:0
	global_store_dwordx2 v21, v[108:109], s[14:15] offset:512
	global_store_dwordx2 v21, v[112:113], s[14:15] offset:1024
	global_store_dwordx2 v21, v[116:117], s[14:15] offset:1536
	v_readlane_b32 s0, v16, 0
	v_readlane_b32 s3, v16, 16
	v_readlane_b32 s10, v16, 32
	v_readlane_b32 s11, v16, 48
	v_mov_b32_e32 v18, s0
	v_add_f32_e32 v18, s3, v18
	v_add_f32_e32 v18, s10, v18
	v_add_f32_e32 v18, s11, v18
	v_mul_f32_e32 v18, 0x49800000, v18
	v_trunc_f32_e32 v18, v18
	v_mul_f32_e32 v19, 0x2f800000, v18
	v_floor_f32_e32 v19, v19
	v_fmac_f32_e32 v18, 0xcf800000, v19
	v_cvt_u32_f32_e32 v18, v18
	v_cvt_u32_f32_e32 v19, v19
	s_mov_b64 exec, 1
	global_store_dwordx2 v23, v[18:19], s[16:17]
	s_mov_b64 exec, -1
	s_add_u32 s14, s14, 0x400000
	s_addc_u32 s15, s15, 0
	s_add_u32 s16, s16, 0x4000
	s_addc_u32 s17, s17, 0
	global_load_dwordx4 v[104:107], v20, s[20:21] offset:0
	global_load_dwordx4 v[108:111], v20, s[20:21] offset:1024
	global_load_dwordx4 v[112:115], v20, s[20:21] offset:2048
	global_load_dwordx4 v[116:119], v20, s[20:21] offset:3072
	s_add_u32 s20, s20, 0x800000
	s_addc_u32 s21, s21, 0
	s_waitcnt vmcnt(27)
; __device__ __forceinline__ unsigned cvt_pk_bf16(float lo, float hi) { const f2_t v = {lo, hi}; const bf2_t b = __builtin_convertvector(v, bf2_t); return __builtin_bit_cast(unsigned, b); }
; __global__ void __launch_bounds__(NTHR, 2) mega(Params p) {
;     ...
;         for (int r = bid * 8 + wid; r < MTOK; r += G * 8) { const int seq = seq_of_row(r);
;             const float* xr = r < 16384 ? p.xp + (size_t)r * DM : p.xs + (size_t)(r - 16384) * DM; float s = 0.f; f32x4 v[4];
; #pragma unroll
;             for (int jj = 0; jj < 4; ++jj) { v[jj] = *(const f32x4*)(xr + jj * 256 + 4 * lane); s += (v[jj][0] * v[jj][0] + v[jj][1] * v[jj][1]) + (v[jj][2] * v[jj][2] + v[jj][3] * v[jj][3]); }
; #pragma unroll
;             for (int o = 32; o >= 1; o >>= 1) s += __shfl_xor(s, o);
;             if (lane == 0) ssb[r] = (u64)(s * SSK);
; #pragma unroll
;             for (int jj = 0; jj < 4; ++jj) { const int c = jj * 256 + 4 * lane; u32x2 wv; float h[4];
; #pragma unroll
;                 for (int j = 0; j < 4; ++j) h[j] = v[jj][j] * (p.norm_g[c + j] * (1.0f + mod[(size_t)seq * MODW + DM + c + j]));
;                 wv.x = cvt_pk_bf16(h[0], h[1]); wv.y = cvt_pk_bf16(h[2], h[3]); *(u32x2*)(xb + (size_t)r * DM + c) = wv; } } }
	v_mul_f32_e32 v16, v0, v0
	v_mul_f32_e32 v18, v1, v1
	v_fmac_f32_e32 v16, v2, v2
	v_fmac_f32_e32 v18, v3, v3
	v_fmac_f32_e32 v16, v4, v4
	v_fmac_f32_e32 v18, v5, v5
	v_fmac_f32_e32 v16, v6, v6
	v_fmac_f32_e32 v18, v7, v7
	v_fmac_f32_e32 v16, v8, v8
	v_fmac_f32_e32 v18, v9, v9
	v_fmac_f32_e32 v16, v10, v10
	v_fmac_f32_e32 v18, v11, v11
	v_fmac_f32_e32 v16, v12, v12
	v_fmac_f32_e32 v18, v13, v13
	v_fmac_f32_e32 v16, v14, v14
	v_fmac_f32_e32 v18, v15, v15
	v_add_f32_e32 v16, v16, v18
	v_pk_mul_f32 v[0:1], v[0:1], v[88:89]
	v_pk_mul_f32 v[2:3], v[2:3], v[90:91]
	v_pk_mul_f32 v[4:5], v[4:5], v[92:93]
	v_pk_mul_f32 v[6:7], v[6:7], v[94:95]
	v_add_f32_dpp v16, v16, v16 quad_perm:[1,0,3,2] row_mask:0xf bank_mask:0xf
	v_pk_mul_f32 v[8:9], v[8:9], v[96:97]
	v_pk_mul_f32 v[10:11], v[10:11], v[98:99]
	v_pk_mul_f32 v[12:13], v[12:13], v[100:101]
	v_pk_mul_f32 v[14:15], v[14:15], v[102:103]
	v_add_f32_dpp v16, v16, v16 quad_perm:[2,3,0,1] row_mask:0xf bank_mask:0xf
	v_cvt_pk_bf16_f32 v0, v0, v1
	v_cvt_pk_bf16_f32 v1, v2, v3
	v_cvt_pk_bf16_f32 v4, v4, v5
	v_cvt_pk_bf16_f32 v5, v6, v7
	v_add_f32_dpp v16, v16, v16 row_ror:4 row_mask:0xf bank_mask:0xf
	v_cvt_pk_bf16_f32 v8, v8, v9
	v_cvt_pk_bf16_f32 v9, v10, v11
	v_cvt_pk_bf16_f32 v12, v12, v13
	v_cvt_pk_bf16_f32 v13, v14, v15
	v_add_f32_dpp v16, v16, v16 row_ror:8 row_mask:0xf bank_mask:0xf
	global_store_dwordx2 v21, v[0:1], s[14:15] offset:0
	global_store_dwordx2 v21, v[4:5], s[14:15] offset:512
	global_store_dwordx2 v21, v[8:9], s[14:15] offset:1024
	global_store_dwordx2 v21, v[12:13], s[14:15] offset:1536
	v_readlane_b32 s0, v16, 0
	v_readlane_b32 s3, v16, 16
	v_readlane_b32 s10, v16, 32
	v_readlane_b32 s11, v16, 48
	v_mov_b32_e32 v18, s0
	v_add_f32_e32 v18, s3, v18
	v_add_f32_e32 v18, s10, v18
	v_add_f32_e32 v18, s11, v18
	v_mul_f32_e32 v18, 0x49800000, v18
	v_trunc_f32_e32 v18, v18
	v_mul_f32_e32 v19, 0x2f800000, v18
	v_floor_f32_e32 v19, v19
	v_fmac_f32_e32 v18, 0xcf800000, v19
	v_cvt_u32_f32_e32 v18, v18
	v_cvt_u32_f32_e32 v19, v19
	s_mov_b64 exec, 1
	global_store_dwordx2 v23, v[18:19], s[16:17]
	s_mov_b64 exec, -1
	s_add_u32 s14, s14, 0x400000
	s_addc_u32 s15, s15, 0
	s_add_u32 s16, s16, 0x4000
	s_addc_u32 s17, s17, 0
	global_load_dwordx4 v[0:3], v20, s[20:21] offset:0
	global_load_dwordx4 v[4:7], v20, s[20:21] offset:1024
	global_load_dwordx4 v[8:11], v20, s[20:21] offset:2048
	global_load_dwordx4 v[12:15], v20, s[20:21] offset:3072
	s_add_u32 s20, s20, 0x800000
	s_addc_u32 s21, s21, 0
	s_waitcnt vmcnt(27)
	v_mul_f32_e32 v16, v24, v24
	v_mul_f32_e32 v18, v25, v25
	v_fmac_f32_e32 v16, v26, v26
	v_fmac_f32_e32 v18, v27, v27
	v_fmac_f32_e32 v16, v28, v28
	v_fmac_f32_e32 v18, v29, v29
	v_fmac_f32_e32 v16, v30, v30
	v_fmac_f32_e32 v18, v31, v31
	v_fmac_f32_e32 v16, v32, v32
	v_fmac_f32_e32 v18, v33, v33
	v_fmac_f32_e32 v16, v34, v34
	v_fmac_f32_e32 v18, v35, v35
	v_fmac_f32_e32 v16, v36, v36
	v_fmac_f32_e32 v18, v37, v37
	v_fmac_f32_e32 v16, v38, v38
	v_fmac_f32_e32 v18, v39, v39
	v_add_f32_e32 v16, v16, v18
	v_pk_mul_f32 v[24:25], v[24:25], v[88:89]
	v_pk_mul_f32 v[26:27], v[26:27], v[90:91]
	v_pk_mul_f32 v[28:29], v[28:29], v[92:93]
	v_pk_mul_f32 v[30:31], v[30:31], v[94:95]
	v_add_f32_dpp v16, v16, v16 quad_perm:[1,0,3,2] row_mask:0xf bank_mask:0xf
	v_pk_mul_f32 v[32:33], v[32:33], v[96:97]
	v_pk_mul_f32 v[34:35], v[34:35], v[98:99]
	v_pk_mul_f32 v[36:37], v[36:37], v[100:101]
	v_pk_mul_f32 v[38:39], v[38:39], v[102:103]
	v_add_f32_dpp v16, v16, v16 quad_perm:[2,3,0,1] row_mask:0xf bank_mask:0xf
	v_cvt_pk_bf16_f32 v24, v24, v25
	v_cvt_pk_bf16_f32 v25, v26, v27
	v_cvt_pk_bf16_f32 v28, v28, v29
	v_cvt_pk_bf16_f32 v29, v30, v31
	v_add_f32_dpp v16, v16, v16 row_ror:4 row_mask:0xf bank_mask:0xf
	v_cvt_pk_bf16_f32 v32, v32, v33
	v_cvt_pk_bf16_f32 v33, v34, v35
	v_cvt_pk_bf16_f32 v36, v36, v37
	v_cvt_pk_bf16_f32 v37, v38, v39
	v_add_f32_dpp v16, v16, v16 row_ror:8 row_mask:0xf bank_mask:0xf
	global_store_dwordx2 v21, v[24:25], s[14:15] offset:0
	global_store_dwordx2 v21, v[28:29], s[14:15] offset:512
	global_store_dwordx2 v21, v[32:33], s[14:15] offset:1024
	global_store_dwordx2 v21, v[36:37], s[14:15] offset:1536
	v_readlane_b32 s0, v16, 0
	v_readlane_b32 s3, v16, 16
	v_readlane_b32 s10, v16, 32
	v_readlane_b32 s11, v16, 48
	v_mov_b32_e32 v18, s0
	v_add_f32_e32 v18, s3, v18
	v_add_f32_e32 v18, s10, v18
	v_add_f32_e32 v18, s11, v18
	v_mul_f32_e32 v18, 0x49800000, v18
	v_trunc_f32_e32 v18, v18
	v_mul_f32_e32 v19, 0x2f800000, v18
	v_floor_f32_e32 v19, v19
	v_fmac_f32_e32 v18, 0xcf800000, v19
	v_cvt_u32_f32_e32 v18, v18
	v_cvt_u32_f32_e32 v19, v19
	s_mov_b64 exec, 1
	global_store_dwordx2 v23, v[18:19], s[16:17]
	s_mov_b64 exec, -1
	s_add_u32 s14, s14, 0x400000
	s_addc_u32 s15, s15, 0
	s_add_u32 s16, s16, 0x4000
	s_addc_u32 s17, s17, 0
	global_load_dwordx4 v[24:27], v20, s[20:21] offset:0
	global_load_dwordx4 v[28:31], v20, s[20:21] offset:1024
	global_load_dwordx4 v[32:35], v20, s[20:21] offset:2048
	global_load_dwordx4 v[36:39], v20, s[20:21] offset:3072
	s_add_u32 s20, s20, 0x800000
	s_addc_u32 s21, s21, 0
	s_waitcnt vmcnt(27)
; __device__ __forceinline__ unsigned cvt_pk_bf16(float lo, float hi) { const f2_t v = {lo, hi}; const bf2_t b = __builtin_convertvector(v, bf2_t); return __builtin_bit_cast(unsigned, b); }
; __global__ void __launch_bounds__(NTHR, 2) mega(Params p) {
;     ...
;         for (int r = bid * 8 + wid; r < MTOK; r += G * 8) { const int seq = seq_of_row(r);
;             const float* xr = r < 16384 ? p.xp + (size_t)r * DM : p.xs + (size_t)(r - 16384) * DM; float s = 0.f; f32x4 v[4];
; #pragma unroll
;             for (int jj = 0; jj < 4; ++jj) { v[jj] = *(const f32x4*)(xr + jj * 256 + 4 * lane); s += (v[jj][0] * v[jj][0] + v[jj][1] * v[jj][1]) + (v[jj][2] * v[jj][2] + v[jj][3] * v[jj][3]); }
; #pragma unroll
;             for (int o = 32; o >= 1; o >>= 1) s += __shfl_xor(s, o);
;             if (lane == 0) ssb[r] = (u64)(s * SSK);
; #pragma unroll
;             for (int jj = 0; jj < 4; ++jj) { const int c = jj * 256 + 4 * lane; u32x2 wv; float h[4];
; #pragma unroll
;                 for (int j = 0; j < 4; ++j) h[j] = v[jj][j] * (p.norm_g[c + j] * (1.0f + mod[(size_t)seq * MODW + DM + c + j]));
;                 wv.x = cvt_pk_bf16(h[0], h[1]); wv.y = cvt_pk_bf16(h[2], h[3]); *(u32x2*)(xb + (size_t)r * DM + c) = wv; } } }
	v_mul_f32_e32 v16, v40, v40
	v_mul_f32_e32 v18, v41, v41
	v_fmac_f32_e32 v16, v42, v42
	v_fmac_f32_e32 v18, v43, v43
	v_fmac_f32_e32 v16, v44, v44
	v_fmac_f32_e32 v18, v45, v45
	v_fmac_f32_e32 v16, v46, v46
	v_fmac_f32_e32 v18, v47, v47
	v_fmac_f32_e32 v16, v48, v48
	v_fmac_f32_e32 v18, v49, v49
	v_fmac_f32_e32 v16, v50, v50
	v_fmac_f32_e32 v18, v51, v51
	v_fmac_f32_e32 v16, v52, v52
	v_fmac_f32_e32 v18, v53, v53
	v_fmac_f32_e32 v16, v54, v54
	v_fmac_f32_e32 v18, v55, v55
	v_add_f32_e32 v16, v16, v18
	v_pk_mul_f32 v[40:41], v[40:41], v[88:89]
	v_pk_mul_f32 v[42:43], v[42:43], v[90:91]
	v_pk_mul_f32 v[44:45], v[44:45], v[92:93]
	v_pk_mul_f32 v[46:47], v[46:47], v[94:95]
	v_add_f32_dpp v16, v16, v16 quad_perm:[1,0,3,2] row_mask:0xf bank_mask:0xf
	v_pk_mul_f32 v[48:49], v[48:49], v[96:97]
	v_pk_mul_f32 v[50:51], v[50:51], v[98:99]
	v_pk_mul_f32 v[52:53], v[52:53], v[100:101]
	v_pk_mul_f32 v[54:55], v[54:55], v[102:103]
	v_add_f32_dpp v16, v16, v16 quad_perm:[2,3,0,1] row_mask:0xf bank_mask:0xf
	v_cvt_pk_bf16_f32 v40, v40, v41
	v_cvt_pk_bf16_f32 v41, v42, v43
	v_cvt_pk_bf16_f32 v44, v44, v45
	v_cvt_pk_bf16_f32 v45, v46, v47
	v_add_f32_dpp v16, v16, v16 row_ror:4 row_mask:0xf bank_mask:0xf
	v_cvt_pk_bf16_f32 v48, v48, v49
	v_cvt_pk_bf16_f32 v49, v50, v51
	v_cvt_pk_bf16_f32 v52, v52, v53
	v_cvt_pk_bf16_f32 v53, v54, v55
	v_add_f32_dpp v16, v16, v16 row_ror:8 row_mask:0xf bank_mask:0xf
	global_store_dwordx2 v21, v[40:41], s[14:15] offset:0
	global_store_dwordx2 v21, v[44:45], s[14:15] offset:512
	global_store_dwordx2 v21, v[48:49], s[14:15] offset:1024
	global_store_dwordx2 v21, v[52:53], s[14:15] offset:1536
	v_readlane_b32 s0, v16, 0
	v_readlane_b32 s3, v16, 16
	v_readlane_b32 s10, v16, 32
	v_readlane_b32 s11, v16, 48
	v_mov_b32_e32 v18, s0
	v_add_f32_e32 v18, s3, v18
	v_add_f32_e32 v18, s10, v18
	v_add_f32_e32 v18, s11, v18
	v_mul_f32_e32 v18, 0x49800000, v18
	v_trunc_f32_e32 v18, v18
	v_mul_f32_e32 v19, 0x2f800000, v18
	v_floor_f32_e32 v19, v19
	v_fmac_f32_e32 v18, 0xcf800000, v19
	v_cvt_u32_f32_e32 v18, v18
	v_cvt_u32_f32_e32 v19, v19
	s_mov_b64 exec, 1
	global_store_dwordx2 v23, v[18:19], s[16:17]
	s_mov_b64 exec, -1
	s_add_u32 s14, s14, 0x400000
	s_addc_u32 s15, s15, 0
	s_add_u32 s16, s16, 0x4000
	s_addc_u32 s17, s17, 0
	global_load_dwordx4 v[40:43], v20, s[20:21] offset:0
	global_load_dwordx4 v[44:47], v20, s[20:21] offset:1024
	global_load_dwordx4 v[48:51], v20, s[20:21] offset:2048
	global_load_dwordx4 v[52:55], v20, s[20:21] offset:3072
	s_add_u32 s20, s20, 0x800000
	s_addc_u32 s21, s21, 0
	s_waitcnt vmcnt(27)
	v_mul_f32_e32 v16, v104, v104
	v_mul_f32_e32 v18, v105, v105
	v_fmac_f32_e32 v16, v106, v106
	v_fmac_f32_e32 v18, v107, v107
	v_fmac_f32_e32 v16, v108, v108
	v_fmac_f32_e32 v18, v109, v109
	v_fmac_f32_e32 v16, v110, v110
	v_fmac_f32_e32 v18, v111, v111
	v_fmac_f32_e32 v16, v112, v112
	v_fmac_f32_e32 v18, v113, v113
	v_fmac_f32_e32 v16, v114, v114
	v_fmac_f32_e32 v18, v115, v115
	v_fmac_f32_e32 v16, v116, v116
	v_fmac_f32_e32 v18, v117, v117
	v_fmac_f32_e32 v16, v118, v118
	v_fmac_f32_e32 v18, v119, v119
	v_add_f32_e32 v16, v16, v18
	v_pk_mul_f32 v[104:105], v[104:105], v[88:89]
	v_pk_mul_f32 v[106:107], v[106:107], v[90:91]
	v_pk_mul_f32 v[108:109], v[108:109], v[92:93]
	v_pk_mul_f32 v[110:111], v[110:111], v[94:95]
	v_add_f32_dpp v16, v16, v16 quad_perm:[1,0,3,2] row_mask:0xf bank_mask:0xf
	v_pk_mul_f32 v[112:113], v[112:113], v[96:97]
	v_pk_mul_f32 v[114:115], v[114:115], v[98:99]
	v_pk_mul_f32 v[116:117], v[116:117], v[100:101]
	v_pk_mul_f32 v[118:119], v[118:119], v[102:103]
	v_add_f32_dpp v16, v16, v16 quad_perm:[2,3,0,1] row_mask:0xf bank_mask:0xf
	v_cvt_pk_bf16_f32 v104, v104, v105
	v_cvt_pk_bf16_f32 v105, v106, v107
	v_cvt_pk_bf16_f32 v108, v108, v109
	v_cvt_pk_bf16_f32 v109, v110, v111
	v_add_f32_dpp v16, v16, v16 row_ror:4 row_mask:0xf bank_mask:0xf
	v_cvt_pk_bf16_f32 v112, v112, v113
	v_cvt_pk_bf16_f32 v113, v114, v115
	v_cvt_pk_bf16_f32 v116, v116, v117
	v_cvt_pk_bf16_f32 v117, v118, v119
	v_add_f32_dpp v16, v16, v16 row_ror:8 row_mask:0xf bank_mask:0xf
	global_store_dwordx2 v21, v[104:105], s[14:15] offset:0
	global_store_dwordx2 v21, v[108:109], s[14:15] offset:512
	global_store_dwordx2 v21, v[112:113], s[14:15] offset:1024
	global_store_dwordx2 v21, v[116:117], s[14:15] offset:1536
	v_readlane_b32 s0, v16, 0
	v_readlane_b32 s3, v16, 16
	v_readlane_b32 s10, v16, 32
	v_readlane_b32 s11, v16, 48
	v_mov_b32_e32 v18, s0
	v_add_f32_e32 v18, s3, v18
	v_add_f32_e32 v18, s10, v18
	v_add_f32_e32 v18, s11, v18
	v_mul_f32_e32 v18, 0x49800000, v18
	v_trunc_f32_e32 v18, v18
	v_mul_f32_e32 v19, 0x2f800000, v18
	v_floor_f32_e32 v19, v19
	v_fmac_f32_e32 v18, 0xcf800000, v19
	v_cvt_u32_f32_e32 v18, v18
	v_cvt_u32_f32_e32 v19, v19
	s_mov_b64 exec, 1
	global_store_dwordx2 v23, v[18:19], s[16:17]
	s_mov_b64 exec, -1
	s_add_u32 s14, s14, 0x400000
	s_addc_u32 s15, s15, 0
	s_add_u32 s16, s16, 0x4000
	s_addc_u32 s17, s17, 0
	global_load_dwordx4 v[104:107], v20, s[20:21] offset:0
	global_load_dwordx4 v[108:111], v20, s[20:21] offset:1024
	global_load_dwordx4 v[112:115], v20, s[20:21] offset:2048
	global_load_dwordx4 v[116:119], v20, s[20:21] offset:3072
	s_add_u32 s20, s20, 0x800000
	s_addc_u32 s21, s21, 0
	s_waitcnt vmcnt(27)
; __device__ __forceinline__ unsigned cvt_pk_bf16(float lo, float hi) { const f2_t v = {lo, hi}; const bf2_t b = __builtin_convertvector(v, bf2_t); return __builtin_bit_cast(unsigned, b); }
; __global__ void __launch_bounds__(NTHR, 2) mega(Params p) {
;     ...
;         for (int r = bid * 8 + wid; r < MTOK; r += G * 8) { const int seq = seq_of_row(r);
;             const float* xr = r < 16384 ? p.xp + (size_t)r * DM : p.xs + (size_t)(r - 16384) * DM; float s = 0.f; f32x4 v[4];
; #pragma unroll
;             for (int jj = 0; jj < 4; ++jj) { v[jj] = *(const f32x4*)(xr + jj * 256 + 4 * lane); s += (v[jj][0] * v[jj][0] + v[jj][1] * v[jj][1]) + (v[jj][2] * v[jj][2] + v[jj][3] * v[jj][3]); }
; #pragma unroll
;             for (int o = 32; o >= 1; o >>= 1) s += __shfl_xor(s, o);
;             if (lane == 0) ssb[r] = (u64)(s * SSK);
; #pragma unroll
;             for (int jj = 0; jj < 4; ++jj) { const int c = jj * 256 + 4 * lane; u32x2 wv; float h[4];
; #pragma unroll
;                 for (int j = 0; j < 4; ++j) h[j] = v[jj][j] * (p.norm_g[c + j] * (1.0f + mod[(size_t)seq * MODW + DM + c + j]));
;                 wv.x = cvt_pk_bf16(h[0], h[1]); wv.y = cvt_pk_bf16(h[2], h[3]); *(u32x2*)(xb + (size_t)r * DM + c) = wv; } } }
	v_mul_f32_e32 v16, v0, v0
	v_mul_f32_e32 v18, v1, v1
	v_fmac_f32_e32 v16, v2, v2
	v_fmac_f32_e32 v18, v3, v3
	v_fmac_f32_e32 v16, v4, v4
	v_fmac_f32_e32 v18, v5, v5
	v_fmac_f32_e32 v16, v6, v6
	v_fmac_f32_e32 v18, v7, v7
	v_fmac_f32_e32 v16, v8, v8
	v_fmac_f32_e32 v18, v9, v9
	v_fmac_f32_e32 v16, v10, v10
	v_fmac_f32_e32 v18, v11, v11
	v_fmac_f32_e32 v16, v12, v12
	v_fmac_f32_e32 v18, v13, v13
	v_fmac_f32_e32 v16, v14, v14
	v_fmac_f32_e32 v18, v15, v15
	v_add_f32_e32 v16, v16, v18
	v_pk_mul_f32 v[0:1], v[0:1], v[88:89]
	v_pk_mul_f32 v[2:3], v[2:3], v[90:91]
	v_pk_mul_f32 v[4:5], v[4:5], v[92:93]
	v_pk_mul_f32 v[6:7], v[6:7], v[94:95]
	v_add_f32_dpp v16, v16, v16 quad_perm:[1,0,3,2] row_mask:0xf bank_mask:0xf
	v_pk_mul_f32 v[8:9], v[8:9], v[96:97]
	v_pk_mul_f32 v[10:11], v[10:11], v[98:99]
	v_pk_mul_f32 v[12:13], v[12:13], v[100:101]
	v_pk_mul_f32 v[14:15], v[14:15], v[102:103]
	v_add_f32_dpp v16, v16, v16 quad_perm:[2,3,0,1] row_mask:0xf bank_mask:0xf
	v_cvt_pk_bf16_f32 v0, v0, v1
	v_cvt_pk_bf16_f32 v1, v2, v3
	v_cvt_pk_bf16_f32 v4, v4, v5
	v_cvt_pk_bf16_f32 v5, v6, v7
	v_add_f32_dpp v16, v16, v16 row_ror:4 row_mask:0xf bank_mask:0xf
	v_cvt_pk_bf16_f32 v8, v8, v9
	v_cvt_pk_bf16_f32 v9, v10, v11
	v_cvt_pk_bf16_f32 v12, v12, v13
	v_cvt_pk_bf16_f32 v13, v14, v15
	v_add_f32_dpp v16, v16, v16 row_ror:8 row_mask:0xf bank_mask:0xf
	global_store_dwordx2 v21, v[0:1], s[14:15] offset:0
	global_store_dwordx2 v21, v[4:5], s[14:15] offset:512
	global_store_dwordx2 v21, v[8:9], s[14:15] offset:1024
	global_store_dwordx2 v21, v[12:13], s[14:15] offset:1536
	v_readlane_b32 s0, v16, 0
	v_readlane_b32 s3, v16, 16
	v_readlane_b32 s10, v16, 32
	v_readlane_b32 s11, v16, 48
	v_mov_b32_e32 v18, s0
	v_add_f32_e32 v18, s3, v18
	v_add_f32_e32 v18, s10, v18
	v_add_f32_e32 v18, s11, v18
	v_mul_f32_e32 v18, 0x49800000, v18
	v_trunc_f32_e32 v18, v18
	v_mul_f32_e32 v19, 0x2f800000, v18
	v_floor_f32_e32 v19, v19
	v_fmac_f32_e32 v18, 0xcf800000, v19
	v_cvt_u32_f32_e32 v18, v18
	v_cvt_u32_f32_e32 v19, v19
	s_mov_b64 exec, 1
	global_store_dwordx2 v23, v[18:19], s[16:17]
	s_mov_b64 exec, -1
	s_add_u32 s14, s14, 0x400000
	s_addc_u32 s15, s15, 0
	s_add_u32 s16, s16, 0x4000
	s_addc_u32 s17, s17, 0
	s_waitcnt vmcnt(23)
	v_mul_f32_e32 v16, v24, v24
	v_mul_f32_e32 v18, v25, v25
	v_fmac_f32_e32 v16, v26, v26
	v_fmac_f32_e32 v18, v27, v27
	v_fmac_f32_e32 v16, v28, v28
	v_fmac_f32_e32 v18, v29, v29
	v_fmac_f32_e32 v16, v30, v30
	v_fmac_f32_e32 v18, v31, v31
	v_fmac_f32_e32 v16, v32, v32
	v_fmac_f32_e32 v18, v33, v33
	v_fmac_f32_e32 v16, v34, v34
	v_fmac_f32_e32 v18, v35, v35
	v_fmac_f32_e32 v16, v36, v36
	v_fmac_f32_e32 v18, v37, v37
	v_fmac_f32_e32 v16, v38, v38
	v_fmac_f32_e32 v18, v39, v39
	v_add_f32_e32 v16, v16, v18
	v_pk_mul_f32 v[24:25], v[24:25], v[88:89]
	v_pk_mul_f32 v[26:27], v[26:27], v[90:91]
	v_pk_mul_f32 v[28:29], v[28:29], v[92:93]
	v_pk_mul_f32 v[30:31], v[30:31], v[94:95]
	v_add_f32_dpp v16, v16, v16 quad_perm:[1,0,3,2] row_mask:0xf bank_mask:0xf
	v_pk_mul_f32 v[32:33], v[32:33], v[96:97]
	v_pk_mul_f32 v[34:35], v[34:35], v[98:99]
	v_pk_mul_f32 v[36:37], v[36:37], v[100:101]
	v_pk_mul_f32 v[38:39], v[38:39], v[102:103]
	v_add_f32_dpp v16, v16, v16 quad_perm:[2,3,0,1] row_mask:0xf bank_mask:0xf
	v_cvt_pk_bf16_f32 v24, v24, v25
	v_cvt_pk_bf16_f32 v25, v26, v27
	v_cvt_pk_bf16_f32 v28, v28, v29
	v_cvt_pk_bf16_f32 v29, v30, v31
	v_add_f32_dpp v16, v16, v16 row_ror:4 row_mask:0xf bank_mask:0xf
	v_cvt_pk_bf16_f32 v32, v32, v33
	v_cvt_pk_bf16_f32 v33, v34, v35
	v_cvt_pk_bf16_f32 v36, v36, v37
	v_cvt_pk_bf16_f32 v37, v38, v39
	v_add_f32_dpp v16, v16, v16 row_ror:8 row_mask:0xf bank_mask:0xf
	global_store_dwordx2 v21, v[24:25], s[14:15] offset:0
	global_store_dwordx2 v21, v[28:29], s[14:15] offset:512
	global_store_dwordx2 v21, v[32:33], s[14:15] offset:1024
	global_store_dwordx2 v21, v[36:37], s[14:15] offset:1536
	v_readlane_b32 s0, v16, 0
	v_readlane_b32 s3, v16, 16
	v_readlane_b32 s10, v16, 32
	v_readlane_b32 s11, v16, 48
	v_mov_b32_e32 v18, s0
	v_add_f32_e32 v18, s3, v18
	v_add_f32_e32 v18, s10, v18
	v_add_f32_e32 v18, s11, v18
	v_mul_f32_e32 v18, 0x49800000, v18
	v_trunc_f32_e32 v18, v18
	v_mul_f32_e32 v19, 0x2f800000, v18
	v_floor_f32_e32 v19, v19
	v_fmac_f32_e32 v18, 0xcf800000, v19
	v_cvt_u32_f32_e32 v18, v18
	v_cvt_u32_f32_e32 v19, v19
	s_mov_b64 exec, 1
	global_store_dwordx2 v23, v[18:19], s[16:17]
	s_mov_b64 exec, -1
	s_add_u32 s14, s14, 0x400000
	s_addc_u32 s15, s15, 0
	s_add_u32 s16, s16, 0x4000
	s_addc_u32 s17, s17, 0
	s_waitcnt vmcnt(19)
; __device__ __forceinline__ unsigned cvt_pk_bf16(float lo, float hi) { const f2_t v = {lo, hi}; const bf2_t b = __builtin_convertvector(v, bf2_t); return __builtin_bit_cast(unsigned, b); }
; __global__ void __launch_bounds__(NTHR, 2) mega(Params p) {
;     ...
;         for (int r = bid * 8 + wid; r < MTOK; r += G * 8) { const int seq = seq_of_row(r);
;             const float* xr = r < 16384 ? p.xp + (size_t)r * DM : p.xs + (size_t)(r - 16384) * DM; float s = 0.f; f32x4 v[4];
; #pragma unroll
;             for (int jj = 0; jj < 4; ++jj) { v[jj] = *(const f32x4*)(xr + jj * 256 + 4 * lane); s += (v[jj][0] * v[jj][0] + v[jj][1] * v[jj][1]) + (v[jj][2] * v[jj][2] + v[jj][3] * v[jj][3]); }
; #pragma unroll
;             for (int o = 32; o >= 1; o >>= 1) s += __shfl_xor(s, o);
;             if (lane == 0) ssb[r] = (u64)(s * SSK);
; #pragma unroll
;             for (int jj = 0; jj < 4; ++jj) { const int c = jj * 256 + 4 * lane; u32x2 wv; float h[4];
; #pragma unroll
;                 for (int j = 0; j < 4; ++j) h[j] = v[jj][j] * (p.norm_g[c + j] * (1.0f + mod[(size_t)seq * MODW + DM + c + j]));
;                 wv.x = cvt_pk_bf16(h[0], h[1]); wv.y = cvt_pk_bf16(h[2], h[3]); *(u32x2*)(xb + (size_t)r * DM + c) = wv; } } }
	v_mul_f32_e32 v16, v40, v40
	v_mul_f32_e32 v18, v41, v41
	v_fmac_f32_e32 v16, v42, v42
	v_fmac_f32_e32 v18, v43, v43
	v_fmac_f32_e32 v16, v44, v44
	v_fmac_f32_e32 v18, v45, v45
	v_fmac_f32_e32 v16, v46, v46
	v_fmac_f32_e32 v18, v47, v47
	v_fmac_f32_e32 v16, v48, v48
	v_fmac_f32_e32 v18, v49, v49
	v_fmac_f32_e32 v16, v50, v50
	v_fmac_f32_e32 v18, v51, v51
	v_fmac_f32_e32 v16, v52, v52
	v_fmac_f32_e32 v18, v53, v53
	v_fmac_f32_e32 v16, v54, v54
	v_fmac_f32_e32 v18, v55, v55
	v_add_f32_e32 v16, v16, v18
	v_pk_mul_f32 v[40:41], v[40:41], v[88:89]
	v_pk_mul_f32 v[42:43], v[42:43], v[90:91]
	v_pk_mul_f32 v[44:45], v[44:45], v[92:93]
	v_pk_mul_f32 v[46:47], v[46:47], v[94:95]
	v_add_f32_dpp v16, v16, v16 quad_perm:[1,0,3,2] row_mask:0xf bank_mask:0xf
	v_pk_mul_f32 v[48:49], v[48:49], v[96:97]
	v_pk_mul_f32 v[50:51], v[50:51], v[98:99]
	v_pk_mul_f32 v[52:53], v[52:53], v[100:101]
	v_pk_mul_f32 v[54:55], v[54:55], v[102:103]
	v_add_f32_dpp v16, v16, v16 quad_perm:[2,3,0,1] row_mask:0xf bank_mask:0xf
	v_cvt_pk_bf16_f32 v40, v40, v41
	v_cvt_pk_bf16_f32 v41, v42, v43
	v_cvt_pk_bf16_f32 v44, v44, v45
	v_cvt_pk_bf16_f32 v45, v46, v47
	v_add_f32_dpp v16, v16, v16 row_ror:4 row_mask:0xf bank_mask:0xf
	v_cvt_pk_bf16_f32 v48, v48, v49
	v_cvt_pk_bf16_f32 v49, v50, v51
	v_cvt_pk_bf16_f32 v52, v52, v53
	v_cvt_pk_bf16_f32 v53, v54, v55
	v_add_f32_dpp v16, v16, v16 row_ror:8 row_mask:0xf bank_mask:0xf
	global_store_dwordx2 v21, v[40:41], s[14:15] offset:0
	global_store_dwordx2 v21, v[44:45], s[14:15] offset:512
	global_store_dwordx2 v21, v[48:49], s[14:15] offset:1024
	global_store_dwordx2 v21, v[52:53], s[14:15] offset:1536
	v_readlane_b32 s0, v16, 0
	v_readlane_b32 s3, v16, 16
	v_readlane_b32 s10, v16, 32
	v_readlane_b32 s11, v16, 48
	v_mov_b32_e32 v18, s0
	v_add_f32_e32 v18, s3, v18
	v_add_f32_e32 v18, s10, v18
	v_add_f32_e32 v18, s11, v18
	v_mul_f32_e32 v18, 0x49800000, v18
	v_trunc_f32_e32 v18, v18
	v_mul_f32_e32 v19, 0x2f800000, v18
	v_floor_f32_e32 v19, v19
	v_fmac_f32_e32 v18, 0xcf800000, v19
	v_cvt_u32_f32_e32 v18, v18
	v_cvt_u32_f32_e32 v19, v19
	s_mov_b64 exec, 1
	global_store_dwordx2 v23, v[18:19], s[16:17]
	s_mov_b64 exec, -1
	s_add_u32 s14, s14, 0x400000
	s_addc_u32 s15, s15, 0
	s_add_u32 s16, s16, 0x4000
	s_addc_u32 s17, s17, 0
	s_waitcnt vmcnt(15)
	v_mul_f32_e32 v16, v104, v104
	v_mul_f32_e32 v18, v105, v105
	v_fmac_f32_e32 v16, v106, v106
	v_fmac_f32_e32 v18, v107, v107
	v_fmac_f32_e32 v16, v108, v108
	v_fmac_f32_e32 v18, v109, v109
	v_fmac_f32_e32 v16, v110, v110
	v_fmac_f32_e32 v18, v111, v111
	v_fmac_f32_e32 v16, v112, v112
	v_fmac_f32_e32 v18, v113, v113
	v_fmac_f32_e32 v16, v114, v114
	v_fmac_f32_e32 v18, v115, v115
	v_fmac_f32_e32 v16, v116, v116
	v_fmac_f32_e32 v18, v117, v117
	v_fmac_f32_e32 v16, v118, v118
	v_fmac_f32_e32 v18, v119, v119
	v_add_f32_e32 v16, v16, v18
	v_pk_mul_f32 v[104:105], v[104:105], v[88:89]
	v_pk_mul_f32 v[106:107], v[106:107], v[90:91]
	v_pk_mul_f32 v[108:109], v[108:109], v[92:93]
	v_pk_mul_f32 v[110:111], v[110:111], v[94:95]
	v_add_f32_dpp v16, v16, v16 quad_perm:[1,0,3,2] row_mask:0xf bank_mask:0xf
	v_pk_mul_f32 v[112:113], v[112:113], v[96:97]
	v_pk_mul_f32 v[114:115], v[114:115], v[98:99]
	v_pk_mul_f32 v[116:117], v[116:117], v[100:101]
	v_pk_mul_f32 v[118:119], v[118:119], v[102:103]
	v_add_f32_dpp v16, v16, v16 quad_perm:[2,3,0,1] row_mask:0xf bank_mask:0xf
	v_cvt_pk_bf16_f32 v104, v104, v105
	v_cvt_pk_bf16_f32 v105, v106, v107
	v_cvt_pk_bf16_f32 v108, v108, v109
	v_cvt_pk_bf16_f32 v109, v110, v111
	v_add_f32_dpp v16, v16, v16 row_ror:4 row_mask:0xf bank_mask:0xf
	v_cvt_pk_bf16_f32 v112, v112, v113
	v_cvt_pk_bf16_f32 v113, v114, v115
	v_cvt_pk_bf16_f32 v116, v116, v117
	v_cvt_pk_bf16_f32 v117, v118, v119
	v_add_f32_dpp v16, v16, v16 row_ror:8 row_mask:0xf bank_mask:0xf
	global_store_dwordx2 v21, v[104:105], s[14:15] offset:0
	global_store_dwordx2 v21, v[108:109], s[14:15] offset:512
	global_store_dwordx2 v21, v[112:113], s[14:15] offset:1024
	global_store_dwordx2 v21, v[116:117], s[14:15] offset:1536
	v_readlane_b32 s0, v16, 0
	v_readlane_b32 s3, v16, 16
	v_readlane_b32 s10, v16, 32
	v_readlane_b32 s11, v16, 48
	v_mov_b32_e32 v18, s0
	v_add_f32_e32 v18, s3, v18
	v_add_f32_e32 v18, s10, v18
	v_add_f32_e32 v18, s11, v18
	v_mul_f32_e32 v18, 0x49800000, v18
	v_trunc_f32_e32 v18, v18
	v_mul_f32_e32 v19, 0x2f800000, v18
	v_floor_f32_e32 v19, v19
	v_fmac_f32_e32 v18, 0xcf800000, v19
	v_cvt_u32_f32_e32 v18, v18
	v_cvt_u32_f32_e32 v19, v19
	s_mov_b64 exec, 1
	global_store_dwordx2 v23, v[18:19], s[16:17]
	s_mov_b64 exec, -1
	s_branch .LBB0_124
; __device__ __forceinline__ unsigned cvt_pk_bf16(float lo, float hi) { const f2_t v = {lo, hi}; const bf2_t b = __builtin_convertvector(v, bf2_t); return __builtin_bit_cast(unsigned, b); }
; __global__ void __launch_bounds__(NTHR, 2) mega(Params p) {
;     ...
;     { const int wid = tid >> 6, lane = tid & 63;
;         for (int r = bid * 8 + wid; r < MTOK; r += G * 8) { const int seq = seq_of_row(r);
;             const float* xr = r < 16384 ? p.xp + (size_t)r * DM : p.xs + (size_t)(r - 16384) * DM; float s = 0.f; f32x4 v[4];
; #pragma unroll
;             for (int jj = 0; jj < 4; ++jj) { v[jj] = *(const f32x4*)(xr + jj * 256 + 4 * lane); s += (v[jj][0] * v[jj][0] + v[jj][1] * v[jj][1]) + (v[jj][2] * v[jj][2] + v[jj][3] * v[jj][3]); }
; #pragma unroll
;             for (int o = 32; o >= 1; o >>= 1) s += __shfl_xor(s, o);
;             if (lane == 0) ssb[r] = (u64)(s * SSK);
; #pragma unroll
;             for (int jj = 0; jj < 4; ++jj) { const int c = jj * 256 + 4 * lane; u32x2 wv; float h[4];
; #pragma unroll
;                 for (int j = 0; j < 4; ++j) h[j] = v[jj][j] * (p.norm_g[c + j] * (1.0f + mod[(size_t)seq * MODW + DM + c + j]));
;                 wv.x = cvt_pk_bf16(h[0], h[1]); wv.y = cvt_pk_bf16(h[2], h[3]); *(u32x2*)(xb + (size_t)r * DM + c) = wv; } } }
.Lxp_orig:
	v_mbcnt_hi_u32_b32 v1, -1, v17
	v_and_b32_e32 v3, 64, v1
	v_add_u32_e32 v3, 64, v3
	v_xor_b32_e32 v4, 32, v1
	v_cmp_lt_i32_e32 vcc, v4, v3
	s_ashr_i32 s13, s12, 31
	v_and_b32_e32 v2, 63, v22
	v_cndmask_b32_e32 v4, v1, v4, vcc
	v_lshlrev_b32_e32 v31, 2, v4
	v_xor_b32_e32 v4, 16, v1
	v_cmp_lt_i32_e32 vcc, v4, v3
	v_readlane_b32 s36, v253, 17
	v_mov_b32_e32 v19, 0
	v_cndmask_b32_e32 v4, v1, v4, vcc
	v_lshlrev_b32_e32 v32, 2, v4
	v_xor_b32_e32 v4, 8, v1
	v_cmp_lt_i32_e32 vcc, v4, v3
	v_lshlrev_b32_e32 v18, 4, v2
	v_readlane_b32 s48, v253, 29
	v_cndmask_b32_e32 v4, v1, v4, vcc
	v_lshlrev_b32_e32 v33, 2, v4
	v_xor_b32_e32 v4, 4, v1
	v_cmp_lt_i32_e32 vcc, v4, v3
	v_readlane_b32 s49, v253, 30
	s_lshl_b32 s10, s34, 3
	v_cndmask_b32_e32 v4, v1, v4, vcc
	v_lshlrev_b32_e32 v34, 2, v4
	v_xor_b32_e32 v4, 2, v1
	v_cmp_lt_i32_e32 vcc, v4, v3
	v_lshl_add_u64 v[20:21], s[48:49], 0, v[18:19]
	v_lshlrev_b32_e32 v18, 3, v2
	v_cndmask_b32_e32 v4, v1, v4, vcc
	v_lshlrev_b32_e32 v35, 2, v4
	v_xor_b32_e32 v4, 1, v1
	v_cmp_lt_i32_e32 vcc, v4, v3
	s_ashr_i32 s11, s10, 31
	v_lshlrev_b32_e32 v16, 2, v2
	v_cndmask_b32_e32 v1, v1, v4, vcc
	v_lshlrev_b32_e32 v36, 2, v1
	v_ashrrev_i32_e32 v1, 31, v0
	v_lshl_add_u64 v[22:23], v[0:1], 0, s[12:13]
	v_lshlrev_b64 v[0:1], 11, v[22:23]
	v_lshl_add_u64 v[0:1], s[4:5], 0, v[0:1]
	v_lshl_add_u64 v[0:1], v[0:1], 0, v[18:19]
	v_lshl_add_u64 v[0:1], s[30:31], 0, v[0:1]
	s_mov_b64 s[12:13], 0x43eca00
	v_lshl_add_u64 v[24:25], v[0:1], 0, s[12:13]
	s_lshl_b64 s[12:13], s[10:11], 11
	s_add_u32 s4, s30, s4
	v_readlane_b32 s37, v253, 18
	v_readlane_b32 s38, v253, 19
	v_readlane_b32 s39, v253, 20
	s_addc_u32 s5, s31, s5
	v_cmp_eq_u32_e64 s[0:1], 0, v2
	v_or_b32_e32 v30, 0x300, v16
	v_or_b32_e32 v37, 0x100, v16
	v_or_b32_e32 v38, 0x200, v16
	v_lshl_add_u64 v[26:27], v[22:23], 3, s[4:5]
	s_lshl_b64 s[14:15], s[10:11], 3
	s_mov_b64 s[16:17], 0
	s_movk_i32 s3, 0x4000
	v_mov_b32_e32 v39, s39
	v_mov_b32_e32 v40, s37
	v_mov_b32_e32 v41, s38
	v_mov_b32_e32 v42, s36
	v_lshlrev_b32_e32 v28, 2, v16
	v_mov_b32_e32 v29, v19
	s_movk_i32 s20, 0x1fff
	s_movk_i32 s21, 0x1000
	s_movk_i32 s22, 0x7fff
	v_mov_b32_e32 v43, 0x3000
	v_mov_b32_e32 v44, 0x1800
	v_readlane_b32 s40, v253, 21
	v_readlane_b32 s41, v253, 22
	v_readlane_b32 s42, v253, 23
	v_readlane_b32 s43, v253, 24
	v_readlane_b32 s44, v253, 25
	v_readlane_b32 s45, v253, 26
	v_readlane_b32 s46, v253, 27
	v_readlane_b32 s47, v253, 28
	v_readlane_b32 s50, v253, 31
	v_readlane_b32 s51, v253, 32
	s_branch .LBB0_122
